# MFMA accumulator clear + first-tile wait/barrier moved behind the tile header (loads stay in two batches)
# speedup vs baseline: 1.0019x; 1.0019x over previous
.LBB0_134:
	s_lshl_b32 s21, s21, 5
	s_and_b32 s21, s21, 0x60
	s_add_i32 m0, s14, 0x18000
	v_lshl_add_u64 v[6:7], v[6:7], 0, s[88:89]
	s_lshl_b32 s24, s20, 13
	s_lshl_b32 s25, s21, 7
	s_waitcnt vmcnt(2)
	s_barrier
	global_load_lds_dwordx4 v[6:7], off
	v_lshl_add_u64 v[4:5], v[4:5], 0, s[88:89]
	s_add_i32 m0, s14, 0x1a000
	s_add_i32 s27, s14, 0x8000
	s_add_i32 s28, s14, 0xa000
	global_load_lds_dwordx4 v[4:5], off
	v_lshl_add_u64 v[0:1], v[0:1], 0, s[88:89]
	s_mov_b32 m0, s27
	s_add_u32 s22, s44, 0x40080
	global_load_lds_dwordx4 v[0:1], off
	v_lshl_add_u64 v[0:1], v[2:3], 0, s[88:89]
	s_mov_b32 m0, s28
	s_addc_u32 s23, s45, 0
	global_load_lds_dwordx4 v[0:1], off
	s_add_i32 m0, s14, 0x1c000
	v_lshl_add_u64 v[0:1], s[22:23], 0, v[196:197]
	global_load_lds_dwordx4 v[0:1], off
	v_lshl_add_u64 v[0:1], s[22:23], 0, v[152:153]
	s_add_i32 m0, s14, 0x1e000
	v_bfe_u32 v2, v9, 4, 2
	global_load_lds_dwordx4 v[0:1], off
	v_and_b32_e32 v1, 15, v9
	v_lshlrev_b32_e32 v0, 4, v2
	v_lshlrev_b32_e32 v3, 2, v9
	v_lshl_or_b32 v184, s20, 6, v1
	v_lshl_or_b32 v1, v1, 6, v0
	v_and_b32_e32 v3, 32, v3
	v_readlane_b32 s22, v249, 56
	v_bitop3_b32 v4, v1, s24, v3 bitop3:0xde
	v_bitop3_b32 v185, v1, s25, v3 bitop3:0xde
	v_mov_b32_e32 v1, v197
	v_readlane_b32 s23, v249, 57
	s_cmpk_lt_u32 s19, 0x100
	s_sext_i32_i16 s33, s18
	v_lshl_add_u64 v[158:159], s[22:23], 0, v[0:1]
	v_lshlrev_b32_e32 v0, 14, v13
	v_and_b32_e32 v0, 0xffff8000, v0
	v_lshl_add_u32 v0, v12, 11, v0
	v_and_b32_e32 v1, 1, v13
	v_lshl_or_b32 v0, v1, 6, v0
	v_lshl_add_u32 v160, v14, 1, v0
	v_lshlrev_b32_e32 v0, 14, v8
	v_and_b32_e32 v0, 0xffff8000, v0
	v_lshl_add_u32 v0, v10, 11, v0
	v_and_b32_e32 v1, 1, v8
	v_lshl_or_b32 v0, v1, 6, v0
	s_cselect_b64 s[18:19], -1, 0
	v_lshl_or_b32 v186, v2, 3, s21
	v_mov_b32_e32 v161, v197
	v_lshl_add_u32 v162, v11, 1, v0
	v_mov_b32_e32 v163, v197
	s_mov_b32 s29, 0
	v_add_u32_e32 v187, 0, v4
	v_mov_b64_e32 v[164:165], s[36:37]
	s_branch .LBB0_137

.LBB0_406:
	s_add_i32 m0, s15, 0x18000
	v_lshl_add_u64 v[0:1], v[0:1], 0, s[88:89]
	s_waitcnt vmcnt(2)
	s_barrier
	global_load_lds_dwordx4 v[0:1], off
	v_lshl_add_u64 v[0:1], v[2:3], 0, s[88:89]
	s_add_i32 m0, s15, 0x1a000
	s_add_i32 s26, s15, 0x8000
	global_load_lds_dwordx4 v[0:1], off
	v_lshl_add_u64 v[0:1], v[8:9], 0, s[88:89]
	s_mov_b32 m0, s26
	s_add_i32 s27, s15, 0xa000
	global_load_lds_dwordx4 v[0:1], off
	v_lshl_add_u64 v[0:1], v[10:11], 0, s[88:89]
	s_mov_b32 m0, s27
	v_and_b32_e32 v2, 15, v12
	global_load_lds_dwordx4 v[0:1], off
	s_add_i32 m0, s15, 0x1c000
	v_lshl_add_u64 v[0:1], v[4:5], 0, s[88:89]
	global_load_lds_dwordx4 v[0:1], off
	v_lshl_add_u64 v[0:1], v[6:7], 0, s[88:89]
	s_add_i32 m0, s15, 0x1e000
	v_lshlrev_b32_e32 v4, 2, v12
	global_load_lds_dwordx4 v[0:1], off
	v_bfe_u32 v1, v12, 4, 2
	v_lshlrev_b32_e32 v0, 4, v1
	s_and_b32 s11, s42, 3
	s_lshr_b32 s91, s2, 6
	v_lshl_or_b32 v194, s43, 6, v2
	v_lshl_or_b32 v2, v2, 6, v0
	s_lshl_b32 s2, s43, 13
	v_and_b32_e32 v4, 32, v4
	v_bitop3_b32 v5, v2, s2, v4 bitop3:0xde
	s_lshl_b32 s2, s11, 12
	s_add_i32 s99, s91, -2
	v_lshlrev_b32_e32 v3, 3, v1
	v_bitop3_b32 v195, v2, s2, v4 bitop3:0xde
	s_cmpk_lt_u32 s33, 0x100
	v_lshlrev_b32_e32 v2, 2, v1
	v_cmp_gt_u32_e64 s[42:43], 2, v1
	v_cmp_eq_u32_e64 s[44:45], 0, v1
	v_lshlrev_b32_e32 v1, 1, v12
	s_cselect_b64 s[80:81], -1, 0
	v_and_b32_e32 v196, 32, v1
	s_lshl_b32 s93, s46, 2
	v_mov_b32_e32 v1, v197
	v_lshl_add_u64 v[166:167], s[8:9], 0, v[0:1]
	v_cvt_f32_ubyte0_e32 v0, s93
	v_rcp_iflag_f32_e32 v0, v0
	s_lshl_b32 s2, s46, 3
	v_readlane_b32 s50, v251, 13
	s_cmp_eq_u32 s11, 0
	v_mul_f32_e32 v0, 0x4f7ffffe, v0
	v_cvt_u32_f32_e32 v0, v0
	v_readlane_b32 s51, v251, 14
	s_cselect_b64 s[8:9], -1, 0
	s_and_b64 s[8:9], s[48:49], s[8:9]
	v_lshl_add_u64 v[162:163], s[50:51], 0, v[196:197]
	v_readlane_b32 s50, v251, 15
	v_readlane_b32 s51, v251, 16
	s_or_b64 s[82:83], s[34:35], s[8:9]
	s_sub_i32 s8, 0, s93
	v_readfirstlane_b32 s9, v0
	v_add_u32_e32 v0, v15, v13
	v_lshl_add_u64 v[164:165], s[50:51], 0, v[196:197]
	s_mul_i32 s8, s8, s9
	v_add_lshl_u32 v196, v0, v14, 1
	v_add_u32_e32 v0, v18, v16
	s_mul_hi_u32 s8, s9, s8
	v_lshl_add_u64 v[168:169], s[12:13], 0, v[196:197]
	v_add_lshl_u32 v196, v0, v17, 1
	s_mov_b32 s33, 0
	s_mov_b32 s77, s37
	v_cmp_gt_u32_e64 s[46:47], s19, v2
	s_mov_b32 s19, s18
	v_lshl_or_b32 v204, s11, 5, v3
	s_add_i32 s94, s9, s8
	v_lshl_add_u64 v[170:171], s[12:13], 0, v[196:197]
	v_add_u32_e32 v205, 0, v5
	s_branch .LBB0_409

.LBB0_841:
	v_bfe_u32 v19, v18, 4, 2
	v_and_b32_e32 v20, 15, v18
	v_lshlrev_b32_e32 v22, 4, v19
	v_lshlrev_b32_e32 v18, 2, v18
	s_and_b32 s27, s23, 3
	s_lshr_b32 s28, s20, 6
	s_waitcnt vmcnt(0)
	v_lshl_or_b32 v144, s21, 6, v20
	v_lshl_or_b32 v20, v20, 6, v22
	s_lshl_b32 s20, s21, 13
	v_and_b32_e32 v18, 32, v18
	v_bitop3_b32 v22, v20, s20, v18 bitop3:0xde
	s_lshl_b32 s20, s27, 12
	v_bitop3_b32 v145, v20, s20, v18 bitop3:0xde
	v_readlane_b32 s20, v249, 56
	v_readlane_b32 s21, v249, 57
	s_add_u32 s20, s20, 0x100000
	s_addc_u32 s21, s21, 0
	s_add_i32 m0, s14, 0x18000
	v_lshl_add_u64 v[0:1], v[0:1], 0, s[88:89]
	s_waitcnt vmcnt(2)
	s_barrier
	global_load_lds_dwordx4 v[0:1], off
	v_lshl_add_u64 v[0:1], v[2:3], 0, s[88:89]
	s_add_i32 m0, s14, 0x1a000
	s_add_i32 s29, s14, 0x8000
	global_load_lds_dwordx4 v[0:1], off
	v_lshl_add_u64 v[0:1], v[8:9], 0, s[88:89]
	s_mov_b32 m0, s29
	s_add_i32 s33, s14, 0xa000
	global_load_lds_dwordx4 v[0:1], off
	v_lshl_add_u64 v[0:1], v[10:11], 0, s[88:89]
	s_mov_b32 m0, s33
	s_add_i32 s48, s28, -2
	global_load_lds_dwordx4 v[0:1], off
	s_add_i32 m0, s14, 0x1c000
	v_lshl_add_u64 v[0:1], v[4:5], 0, s[88:89]
	global_load_lds_dwordx4 v[0:1], off
	v_lshl_add_u64 v[0:1], v[6:7], 0, s[88:89]
	s_add_i32 m0, s14, 0x1e000
	v_lshlrev_b32_e32 v21, 3, v19
	global_load_lds_dwordx4 v[0:1], off
	v_add_u32_e32 v0, v17, v15
	v_add_lshl_u32 v0, v0, v16, 1
	v_mov_b32_e32 v1, v197
	v_lshl_add_u64 v[134:135], s[12:13], 0, v[0:1]
	v_add_u32_e32 v0, v14, v12
	s_cmpk_lt_u32 s22, 0x100
	v_add_lshl_u32 v0, v0, v13, 1
	v_lshl_or_b32 v146, s27, 5, v21
	s_cselect_b64 s[22:23], -1, 0
	s_mov_b32 s49, 0
	v_cmp_eq_u32_e64 s[40:41], 0, v19
	v_lshl_add_u64 v[136:137], s[12:13], 0, v[0:1]
	v_add_u32_e32 v147, 0, v22
	v_readlane_b32 s36, v250, 9
	v_readlane_b32 s51, v250, 8
	s_branch .LBB0_844
